# sc_conv: inner row loop fully unrolled, all 32 row loads issued before the halo handling, exact counted waits
# speedup vs baseline: 1.0017x; 1.0017x over previous
; __device__ __forceinline__ void phase_sc_conv(const Args& a, int j) {
;     ...
;     for (int it = gt; it < NITEMS; it += NGT) {
;         const int c8 = it % C8, rb = it / C8, c0 = c8 * 8, row0 = rb * RUN;
;         float w0[8], w1[8], w2[8];
; #pragma unroll
;         for (int h = 0; h < 2; ++h) { const f32x4 t0 = *(const f32x4*)(cw + c0 + 4 * h), t1 = *(const f32x4*)(cw + 1024 + c0 + 4 * h), t2 = *(const f32x4*)(cw + 2048 + c0 + 4 * h);
; #pragma unroll
;             for (int e = 0; e < 4; ++e) { w0[4 * h + e] = t0[e]; w1[4 * h + e] = t1[e]; w2[4 * h + e] = t2[e]; } }
;         float g0[8], g1[8];
;         if ((row0 & (SEQ_ - 1)) == 0) {
; #pragma unroll
;             for (int e = 0; e < 8; ++e) { g0[e] = 0.f; g1[e] = 0.f; }
;         } else {
;             unpack8(*(const uint4*)(BIG + (size_t)(row0 - 2) * LD + 1024 + c0), g0); unpack8(*(const uint4*)(BIG + (size_t)(row0 - 1) * LD + 1024 + c0), g1);
;         }
; #pragma unroll 4
;         for (int r = 0; r < RUN; ++r) {
;             bf16_t* p = BIG + (size_t)(row0 + r) * LD + c0;
;             float gb[8], cur[8], o[8];
;             unpack8(*(const uint4*)p, gb); unpack8(*(const uint4*)(p + 1024), cur);
.LBB0_757:
	s_waitcnt vmcnt(0)
	v_ashrrev_i32_e32 v2, 31, v1
	v_lshrrev_b32_e32 v2, 25, v2
	v_add_u32_e32 v2, v1, v2
	v_and_b32_e32 v4, 0x1fffff80, v2
	v_sub_u32_e32 v4, v1, v4
	v_lshlrev_b32_e32 v4, 3, v4
	v_ashrrev_i32_e32 v5, 31, v4
	v_lshlrev_b64 v[10:11], 2, v[4:5]
	v_lshl_add_u64 v[14:15], s[4:5], 0, v[10:11]
	v_lshl_add_u64 v[22:23], s[6:7], 0, v[10:11]
	v_lshl_add_u64 v[30:31], s[8:9], 0, v[10:11]
	global_load_dwordx4 v[10:13], v[14:15], off offset:16
	s_nop 0
	global_load_dwordx4 v[14:17], v[14:15], off
	s_nop 0
	global_load_dwordx4 v[18:21], v[22:23], off offset:16
	s_nop 0
	global_load_dwordx4 v[22:25], v[22:23], off
	s_nop 0
	global_load_dwordx4 v[26:29], v[30:31], off offset:16
	s_nop 0
	global_load_dwordx4 v[30:33], v[30:31], off
	v_ashrrev_i32_e32 v2, 7, v2
	v_lshlrev_b32_e32 v38, 4, v2
	v_cmp_ne_u32_sdwa s[2:3], v2, v3 src0_sel:BYTE_0 src1_sel:DWORD
	v_mov_b32_e32 v2, v3
	v_mov_b32_e32 v62, 0
	v_ashrrev_i32_e32 v39, 31, v38
	v_mov_b64_e32 v[36:37], v[2:3]
	v_mov_b64_e32 v[34:35], v[2:3]
	v_mov_b32_e32 v67, 0
	v_mov_b32_e32 v65, 0
	v_mov_b32_e32 v66, 0
	v_mov_b32_e32 v63, 0
	v_mov_b32_e32 v64, 0
	v_mov_b32_e32 v61, 0
	v_mov_b32_e32 v68, 0
	v_mov_b32_e32 v44, 0
	v_mov_b32_e32 v43, 0
	v_mov_b32_e32 v42, 0
	v_mov_b32_e32 v2, 0
	v_lshlrev_b64 v[236:237], 12, v[38:39]
	v_lshl_add_u64 v[236:237], v[4:5], 1, v[236:237]
	v_lshl_add_u64 v[236:237], s[30:31], 0, v[236:237]
	s_mov_b32 s12, s18
	s_mov_b32 s13, 0
	v_lshl_add_u64 v[232:233], v[236:237], 0, s[12:13]
	s_mov_b32 s12, 0x9303000
	v_lshl_add_u64 v[234:235], v[236:237], 0, s[12:13]
	global_load_dwordx4 v[76:79], v[232:233], off offset:-4096
	global_load_dwordx4 v[80:83], v[232:233], off offset:-2048
	global_load_dwordx4 v[84:87], v[232:233], off
	global_load_dwordx4 v[88:91], v[232:233], off offset:2048
	global_load_dwordx4 v[92:95], v[234:235], off offset:-4096
	global_load_dwordx4 v[96:99], v[234:235], off offset:-2048
	global_load_dwordx4 v[100:103], v[234:235], off
	global_load_dwordx4 v[104:107], v[234:235], off offset:2048
	s_add_u32 s12, s18, 0x4000
	s_mov_b32 s13, 0
	v_lshl_add_u64 v[232:233], v[236:237], 0, s[12:13]
	s_mov_b32 s12, 0x9307000
	v_lshl_add_u64 v[234:235], v[236:237], 0, s[12:13]
	global_load_dwordx4 v[112:115], v[232:233], off offset:-4096
	global_load_dwordx4 v[116:119], v[232:233], off offset:-2048
	global_load_dwordx4 v[120:123], v[232:233], off
	global_load_dwordx4 v[124:127], v[232:233], off offset:2048
	global_load_dwordx4 v[128:131], v[234:235], off offset:-4096
	global_load_dwordx4 v[132:135], v[234:235], off offset:-2048
	global_load_dwordx4 v[136:139], v[234:235], off
	global_load_dwordx4 v[140:143], v[234:235], off offset:2048
	s_add_u32 s12, s18, 0x8000
	s_mov_b32 s13, 0
	v_lshl_add_u64 v[232:233], v[236:237], 0, s[12:13]
	s_mov_b32 s12, 0x930b000
	v_lshl_add_u64 v[234:235], v[236:237], 0, s[12:13]
	global_load_dwordx4 v[144:147], v[232:233], off offset:-4096
	global_load_dwordx4 v[148:151], v[232:233], off offset:-2048
	global_load_dwordx4 v[152:155], v[232:233], off
	global_load_dwordx4 v[156:159], v[232:233], off offset:2048
	global_load_dwordx4 v[160:163], v[234:235], off offset:-4096
	global_load_dwordx4 v[164:167], v[234:235], off offset:-2048
	global_load_dwordx4 v[176:179], v[234:235], off
	global_load_dwordx4 v[180:183], v[234:235], off offset:2048
	s_add_u32 s12, s18, 0xc000
	s_mov_b32 s13, 0
	v_lshl_add_u64 v[232:233], v[236:237], 0, s[12:13]
	s_mov_b32 s12, 0x930f000
	v_lshl_add_u64 v[234:235], v[236:237], 0, s[12:13]
	global_load_dwordx4 v[184:187], v[232:233], off offset:-4096
	global_load_dwordx4 v[188:191], v[232:233], off offset:-2048
	global_load_dwordx4 v[192:195], v[232:233], off
	global_load_dwordx4 v[196:199], v[232:233], off offset:2048
	global_load_dwordx4 v[200:203], v[234:235], off offset:-4096
	global_load_dwordx4 v[220:223], v[234:235], off offset:-2048
	global_load_dwordx4 v[224:227], v[234:235], off
	global_load_dwordx4 v[228:231], v[234:235], off offset:2048
	s_and_saveexec_b64 s[12:13], s[2:3]
	s_cbranch_execz .LBB0_759
	v_readlane_b32 s2, v253, 16
	v_lshlrev_b64 v[34:35], 12, v[38:39]
	v_readlane_b32 s3, v253, 17
	s_nop 1
	v_lshl_add_u64 v[34:35], s[2:3], 0, v[34:35]
	v_lshl_add_u64 v[40:41], v[4:5], 1, v[34:35]
	v_add_co_u32_e32 v34, vcc, 0xfffff000, v40
	s_nop 1
	v_addc_co_u32_e32 v35, vcc, -1, v41, vcc
	global_load_dwordx4 v[46:49], v[34:35], off offset:-2048
	s_waitcnt vmcnt(0)
	v_lshlrev_b32_e32 v44, 16, v46
	v_and_b32_e32 v43, 0xffff0000, v46
	v_lshlrev_b32_e32 v42, 16, v47
	v_and_b32_e32 v2, 0xffff0000, v47
	v_lshlrev_b32_e32 v36, 16, v48
	v_and_b32_e32 v37, 0xffff0000, v48
	v_lshlrev_b32_e32 v34, 16, v49
	v_and_b32_e32 v35, 0xffff0000, v49
	global_load_dwordx4 v[46:49], v[40:41], off offset:-2048
	s_waitcnt vmcnt(0)
	v_lshlrev_b32_e32 v62, 16, v46
	v_and_b32_e32 v67, 0xffff0000, v46
	v_lshlrev_b32_e32 v65, 16, v47
	v_and_b32_e32 v66, 0xffff0000, v47
	v_lshlrev_b32_e32 v63, 16, v48
	v_and_b32_e32 v64, 0xffff0000, v48
	v_lshlrev_b32_e32 v61, 16, v49
	v_and_b32_e32 v68, 0xffff0000, v49
; __device__ __forceinline__ uint4 pack8(const float* f) { uint4 o; o.x = pk2(f[0], f[1]); o.y = pk2(f[2], f[3]); o.z = pk2(f[4], f[5]); o.w = pk2(f[6], f[7]); return o; }
; __device__ __forceinline__ void phase_sc_conv(const Args& a, int j) {
;     ...
; #pragma unroll 4
;         for (int r = 0; r < RUN; ++r) {
;             bf16_t* p = BIG + (size_t)(row0 + r) * LD + c0;
;             float gb[8], cur[8], o[8];
;             unpack8(*(const uint4*)p, gb); unpack8(*(const uint4*)(p + 1024), cur);
; #pragma unroll
;             for (int e = 0; e < 8; ++e) { o[e] = gb[e] * (w0[e] * g0[e] + w1[e] * g1[e] + w2[e] * cur[e]); g0[e] = g1[e]; g1[e] = cur[e]; }
;             *(uint4*)p = pack8(o);
;         }
.LBB0_759:
	s_or_b64 exec, exec, s[12:13]
	v_lshlrev_b64 v[38:39], 12, v[38:39]
	v_lshl_add_u64 v[4:5], v[4:5], 1, v[38:39]
	v_lshl_add_u64 v[4:5], s[30:31], 0, v[4:5]
	s_mov_b64 s[12:13], 0
	v_lshl_add_u64 v[38:39], v[4:5], 0, s[12:13]
	v_add_co_u32_e32 v50, vcc, s26, v38
	s_mov_b32 s2, 0x9302000
	s_nop 0
	v_addc_co_u32_e32 v51, vcc, 0, v39, vcc
	v_add_co_u32_e32 v40, vcc, s18, v38
	s_add_u32 s12, s12, 0x4000
	s_nop 0
	v_addc_co_u32_e32 v41, vcc, 0, v39, vcc
	v_add_co_u32_e32 v108, vcc, 0x9303000, v38
	s_nop 1
	v_addc_co_u32_e32 v109, vcc, 0, v39, vcc
	s_addc_u32 s13, s13, 0
	s_waitcnt vmcnt(31)
	v_lshlrev_b32_e32 v53, 16, v76
	v_and_b32_e32 v54, 0xffff0000, v76
	v_lshlrev_b32_e32 v69, 16, v77
	v_and_b32_e32 v70, 0xffff0000, v77
	v_lshlrev_b32_e32 v71, 16, v78
	v_and_b32_e32 v72, 0xffff0000, v78
	v_lshlrev_b32_e32 v73, 16, v79
	v_and_b32_e32 v74, 0xffff0000, v79
	s_waitcnt vmcnt(30)
	v_lshlrev_b32_e32 v60, 16, v80
	v_and_b32_e32 v59, 0xffff0000, v80
	v_mul_f32_e32 v46, v22, v62
	v_fmac_f32_e32 v46, v14, v44
	v_mul_f32_e32 v44, v23, v67
	v_fmac_f32_e32 v46, v30, v60
	v_fmac_f32_e32 v44, v15, v43
	v_mul_f32_e32 v43, v46, v53
	v_mul_f32_e32 v46, v24, v65
	v_lshlrev_b32_e32 v58, 16, v81
	v_fmac_f32_e32 v46, v16, v42
	v_mul_f32_e32 v42, v25, v66
	v_fmac_f32_e32 v46, v32, v58
	v_fmac_f32_e32 v42, v17, v2
	v_mul_f32_e32 v2, v46, v69
	v_mul_f32_e32 v46, v18, v63
	v_lshlrev_b32_e32 v56, 16, v82
	v_fmac_f32_e32 v46, v10, v36
	v_mul_f32_e32 v36, v19, v64
	v_fmac_f32_e32 v46, v26, v56
	v_fmac_f32_e32 v36, v11, v37
	v_mul_f32_e32 v37, v46, v71
	v_mul_f32_e32 v46, v20, v61
	v_and_b32_e32 v55, 0xffff0000, v82
	v_fmac_f32_e32 v46, v12, v34
	v_mul_f32_e32 v34, v21, v68
	v_and_b32_e32 v57, 0xffff0000, v81
	v_lshlrev_b32_e32 v52, 16, v83
	v_and_b32_e32 v45, 0xffff0000, v83
	v_fmac_f32_e32 v36, v27, v55
	v_fmac_f32_e32 v34, v13, v35
	v_fmac_f32_e32 v44, v31, v59
	v_fmac_f32_e32 v42, v33, v57
	v_mul_f32_e32 v36, v36, v72
	v_fmac_f32_e32 v46, v28, v52
	v_fmac_f32_e32 v34, v29, v45
	v_mul_f32_e32 v44, v44, v54
	v_mul_f32_e32 v42, v42, v70
	v_mul_f32_e32 v46, v46, v73
	v_mul_f32_e32 v47, v34, v74
	v_cvt_pk_bf16_f32 v34, v43, v44
	v_cvt_pk_bf16_f32 v35, v2, v42
	v_cvt_pk_bf16_f32 v36, v37, v36
	v_cvt_pk_bf16_f32 v37, v46, v47
	global_store_dwordx4 v[40:41], v[34:37], off offset:-4096
	s_waitcnt vmcnt(30)
	v_lshlrev_b32_e32 v2, 16, v84
	v_and_b32_e32 v42, 0xffff0000, v84
	v_lshlrev_b32_e32 v43, 16, v85
	v_and_b32_e32 v44, 0xffff0000, v85
	v_lshlrev_b32_e32 v69, 16, v86
	v_and_b32_e32 v70, 0xffff0000, v86
	v_lshlrev_b32_e32 v71, 16, v87
	v_and_b32_e32 v72, 0xffff0000, v87
	s_waitcnt vmcnt(29)
	v_lshlrev_b32_e32 v54, 16, v88
	v_and_b32_e32 v53, 0xffff0000, v88
	v_lshlrev_b32_e32 v51, 16, v89
	v_and_b32_e32 v50, 0xffff0000, v89
	v_mul_f32_e32 v34, v22, v60
	v_mul_f32_e32 v35, v23, v59
	v_fmac_f32_e32 v34, v14, v62
	v_fmac_f32_e32 v35, v15, v67
	v_fmac_f32_e32 v34, v30, v54
	v_fmac_f32_e32 v35, v31, v53
	v_mul_f32_e32 v2, v34, v2
	v_mul_f32_e32 v34, v35, v42
	v_mul_f32_e32 v35, v24, v58
	v_lshlrev_b32_e32 v49, 16, v90
	v_and_b32_e32 v48, 0xffff0000, v90
	v_fmac_f32_e32 v35, v16, v65
	v_mul_f32_e32 v36, v25, v57
	v_fmac_f32_e32 v36, v17, v66
	v_fmac_f32_e32 v35, v32, v51
	v_mul_f32_e32 v42, v19, v55
	v_lshlrev_b32_e32 v47, 16, v91
	v_and_b32_e32 v46, 0xffff0000, v91
	v_mul_f32_e32 v35, v35, v43
	v_fmac_f32_e32 v36, v33, v50
	v_mul_f32_e32 v37, v18, v56
	v_fmac_f32_e32 v42, v11, v64
	v_mul_f32_e32 v43, v20, v52
	v_mul_f32_e32 v36, v36, v44
	v_fmac_f32_e32 v37, v10, v63
	v_fmac_f32_e32 v42, v27, v48
	v_fmac_f32_e32 v43, v12, v61
	v_mul_f32_e32 v44, v21, v45
	v_fmac_f32_e32 v37, v26, v49
	v_mul_f32_e32 v42, v42, v70
	v_fmac_f32_e32 v44, v13, v68
	v_fmac_f32_e32 v43, v28, v47
	v_mul_f32_e32 v37, v37, v69
	v_mul_f32_e32 v43, v43, v71
	v_fmac_f32_e32 v44, v29, v46
	v_cvt_pk_bf16_f32 v34, v2, v34
	v_cvt_pk_bf16_f32 v35, v35, v36
	v_cvt_pk_bf16_f32 v36, v37, v42
	v_add_co_u32_e32 v42, vcc, s2, v38
	v_mul_f32_e32 v44, v44, v72
	v_cvt_pk_bf16_f32 v37, v43, v44
	s_nop 0
	v_addc_co_u32_e32 v43, vcc, 0, v39, vcc
	s_mov_b32 s2, 0x9303000
	v_add_co_u32_e32 v38, vcc, s2, v38
	global_store_dwordx4 v[40:41], v[34:37], off
	s_nop 0
	v_addc_co_u32_e32 v39, vcc, 0, v39, vcc
	s_waitcnt vmcnt(29)
	v_lshlrev_b32_e32 v65, 16, v92
	s_waitcnt vmcnt(28)
	v_lshlrev_b32_e32 v44, 16, v96
	v_and_b32_e32 v43, 0xffff0000, v96
	v_mul_f32_e32 v66, v22, v54
	v_fmac_f32_e32 v66, v14, v60
	v_mul_f32_e32 v60, v23, v53
	v_fmac_f32_e32 v66, v30, v44
	v_fmac_f32_e32 v60, v15, v59
	v_mul_f32_e32 v59, v66, v65
	v_mul_f32_e32 v65, v24, v51
	v_fmac_f32_e32 v65, v16, v58
	v_mul_f32_e32 v58, v25, v50
	v_and_b32_e32 v2, 0xffff0000, v97
	v_fmac_f32_e32 v58, v17, v57
	v_and_b32_e32 v63, 0xffff0000, v93
	v_fmac_f32_e32 v58, v33, v2
	v_mul_f32_e32 v58, v58, v63
	v_mul_f32_e32 v63, v18, v49
	v_fmac_f32_e32 v63, v10, v56
	v_mul_f32_e32 v56, v19, v48
	v_lshlrev_b32_e32 v41, 16, v95
	v_and_b32_e32 v40, 0xffff0000, v95
	v_and_b32_e32 v37, 0xffff0000, v98
	v_fmac_f32_e32 v56, v11, v55
	v_and_b32_e32 v61, 0xffff0000, v94
	v_fmac_f32_e32 v56, v27, v37
	v_mul_f32_e32 v61, v56, v61
	v_mul_f32_e32 v56, v20, v47
	v_lshlrev_b32_e32 v42, 16, v97
	v_fmac_f32_e32 v56, v12, v52
	v_mul_f32_e32 v52, v21, v46
	v_and_b32_e32 v70, 0xffff0000, v92
	v_lshlrev_b32_e32 v64, 16, v93
	v_lshlrev_b32_e32 v62, 16, v94
	v_lshlrev_b32_e32 v36, 16, v98
	v_lshlrev_b32_e32 v34, 16, v99
	v_and_b32_e32 v35, 0xffff0000, v99
	v_fmac_f32_e32 v65, v32, v42
	v_fmac_f32_e32 v52, v13, v45
	v_fmac_f32_e32 v60, v31, v43
	v_mul_f32_e32 v57, v65, v64
	v_fmac_f32_e32 v63, v26, v36
	v_fmac_f32_e32 v56, v28, v34
	v_fmac_f32_e32 v52, v29, v35
	v_mul_f32_e32 v60, v60, v70
	v_mul_f32_e32 v55, v63, v62
	v_mul_f32_e32 v41, v56, v41
	v_mul_f32_e32 v40, v52, v40
	v_cvt_pk_bf16_f32 v56, v59, v60
	v_cvt_pk_bf16_f32 v57, v57, v58
	v_cvt_pk_bf16_f32 v58, v55, v61
	v_cvt_pk_bf16_f32 v59, v41, v40
	global_store_dwordx4 v[38:39], v[56:59], off offset:-4096
	s_waitcnt vmcnt(28)
; __device__ __forceinline__ uint4 pack8(const float* f) { uint4 o; o.x = pk2(f[0], f[1]); o.y = pk2(f[2], f[3]); o.z = pk2(f[4], f[5]); o.w = pk2(f[6], f[7]); return o; }
; __device__ __forceinline__ void phase_sc_conv(const Args& a, int j) {
;     ...
; #pragma unroll 4
;         for (int r = 0; r < RUN; ++r) {
;             bf16_t* p = BIG + (size_t)(row0 + r) * LD + c0;
;             float gb[8], cur[8], o[8];
;             unpack8(*(const uint4*)p, gb); unpack8(*(const uint4*)(p + 1024), cur);
; #pragma unroll
;             for (int e = 0; e < 8; ++e) { o[e] = gb[e] * (w0[e] * g0[e] + w1[e] * g1[e] + w2[e] * cur[e]); g0[e] = g1[e]; g1[e] = cur[e]; }
;             *(uint4*)p = pack8(o);
;         }
	v_lshlrev_b32_e32 v40, 16, v100
	v_and_b32_e32 v41, 0xffff0000, v100
	v_lshlrev_b32_e32 v45, 16, v101
	v_and_b32_e32 v52, 0xffff0000, v101
	v_lshlrev_b32_e32 v55, 16, v102
	v_and_b32_e32 v60, 0xffff0000, v102
	v_lshlrev_b32_e32 v69, 16, v103
	v_and_b32_e32 v70, 0xffff0000, v103
	s_waitcnt vmcnt(27)
	v_lshlrev_b32_e32 v62, 16, v104
	v_and_b32_e32 v67, 0xffff0000, v104
	v_mul_f32_e32 v56, v22, v44
	v_fmac_f32_e32 v56, v14, v54
	v_mul_f32_e32 v54, v23, v43
	v_fmac_f32_e32 v54, v15, v53
	v_mul_f32_e32 v53, v24, v42
	v_fmac_f32_e32 v53, v16, v51
	v_mul_f32_e32 v51, v25, v2
	v_and_b32_e32 v66, 0xffff0000, v105
	v_fmac_f32_e32 v51, v17, v50
	v_fmac_f32_e32 v51, v33, v66
	v_mul_f32_e32 v50, v51, v52
	v_mul_f32_e32 v51, v18, v36
	v_lshlrev_b32_e32 v63, 16, v106
	v_fmac_f32_e32 v51, v10, v49
	v_mul_f32_e32 v49, v19, v37
	v_fmac_f32_e32 v51, v26, v63
	v_fmac_f32_e32 v49, v11, v48
	v_mul_f32_e32 v48, v51, v55
	v_mul_f32_e32 v51, v20, v34
	v_and_b32_e32 v64, 0xffff0000, v106
	v_fmac_f32_e32 v51, v12, v47
	v_mul_f32_e32 v47, v21, v35
	v_lshlrev_b32_e32 v65, 16, v105
	v_lshlrev_b32_e32 v61, 16, v107
	v_and_b32_e32 v68, 0xffff0000, v107
	v_fmac_f32_e32 v49, v27, v64
	v_fmac_f32_e32 v47, v13, v46
	v_fmac_f32_e32 v56, v30, v62
	v_fmac_f32_e32 v54, v31, v67
	v_fmac_f32_e32 v53, v32, v65
	v_mul_f32_e32 v49, v49, v60
	v_fmac_f32_e32 v51, v28, v61
	v_fmac_f32_e32 v47, v29, v68
	v_mul_f32_e32 v40, v56, v40
	v_mul_f32_e32 v41, v54, v41
	v_mul_f32_e32 v45, v53, v45
	v_mul_f32_e32 v51, v51, v69
	v_mul_f32_e32 v52, v47, v70
	v_cvt_pk_bf16_f32 v46, v40, v41
	v_cvt_pk_bf16_f32 v47, v45, v50
	v_cvt_pk_bf16_f32 v48, v48, v49
	v_cvt_pk_bf16_f32 v49, v51, v52
	global_store_dwordx4 v[38:39], v[46:49], off
	v_lshl_add_u64 v[38:39], v[4:5], 0, s[12:13]
	v_add_co_u32_e32 v50, vcc, s26, v38
	s_mov_b32 s2, 0x9302000
	s_nop 0
	v_addc_co_u32_e32 v51, vcc, 0, v39, vcc
	v_add_co_u32_e32 v40, vcc, s18, v38
	s_add_u32 s12, s12, 0x4000
	s_nop 0
	v_addc_co_u32_e32 v41, vcc, 0, v39, vcc
	v_add_co_u32_e32 v108, vcc, 0x9303000, v38
	s_nop 1
	v_addc_co_u32_e32 v109, vcc, 0, v39, vcc
	s_addc_u32 s13, s13, 0
	s_waitcnt vmcnt(27)
	v_lshlrev_b32_e32 v53, 16, v112
	v_and_b32_e32 v54, 0xffff0000, v112
	v_lshlrev_b32_e32 v69, 16, v113
	v_and_b32_e32 v70, 0xffff0000, v113
	v_lshlrev_b32_e32 v71, 16, v114
	v_and_b32_e32 v72, 0xffff0000, v114
	v_lshlrev_b32_e32 v73, 16, v115
	v_and_b32_e32 v74, 0xffff0000, v115
	s_waitcnt vmcnt(26)
	v_lshlrev_b32_e32 v60, 16, v116
	v_and_b32_e32 v59, 0xffff0000, v116
	v_mul_f32_e32 v46, v22, v62
	v_fmac_f32_e32 v46, v14, v44
	v_mul_f32_e32 v44, v23, v67
	v_fmac_f32_e32 v46, v30, v60
	v_fmac_f32_e32 v44, v15, v43
	v_mul_f32_e32 v43, v46, v53
	v_mul_f32_e32 v46, v24, v65
	v_lshlrev_b32_e32 v58, 16, v117
	v_fmac_f32_e32 v46, v16, v42
	v_mul_f32_e32 v42, v25, v66
	v_fmac_f32_e32 v46, v32, v58
	v_fmac_f32_e32 v42, v17, v2
	v_mul_f32_e32 v2, v46, v69
	v_mul_f32_e32 v46, v18, v63
	v_lshlrev_b32_e32 v56, 16, v118
	v_fmac_f32_e32 v46, v10, v36
	v_mul_f32_e32 v36, v19, v64
	v_fmac_f32_e32 v46, v26, v56
	v_fmac_f32_e32 v36, v11, v37
	v_mul_f32_e32 v37, v46, v71
	v_mul_f32_e32 v46, v20, v61
	v_and_b32_e32 v55, 0xffff0000, v118
	v_fmac_f32_e32 v46, v12, v34
	v_mul_f32_e32 v34, v21, v68
	v_and_b32_e32 v57, 0xffff0000, v117
	v_lshlrev_b32_e32 v52, 16, v119
	v_and_b32_e32 v45, 0xffff0000, v119
	v_fmac_f32_e32 v36, v27, v55
	v_fmac_f32_e32 v34, v13, v35
	v_fmac_f32_e32 v44, v31, v59
	v_fmac_f32_e32 v42, v33, v57
	v_mul_f32_e32 v36, v36, v72
	v_fmac_f32_e32 v46, v28, v52
	v_fmac_f32_e32 v34, v29, v45
	v_mul_f32_e32 v44, v44, v54
	v_mul_f32_e32 v42, v42, v70
	v_mul_f32_e32 v46, v46, v73
	v_mul_f32_e32 v47, v34, v74
	v_cvt_pk_bf16_f32 v34, v43, v44
	v_cvt_pk_bf16_f32 v35, v2, v42
	v_cvt_pk_bf16_f32 v36, v37, v36
	v_cvt_pk_bf16_f32 v37, v46, v47
	global_store_dwordx4 v[40:41], v[34:37], off offset:-4096
	s_waitcnt vmcnt(26)
	v_lshlrev_b32_e32 v2, 16, v120
	v_and_b32_e32 v42, 0xffff0000, v120
	v_lshlrev_b32_e32 v43, 16, v121
	v_and_b32_e32 v44, 0xffff0000, v121
	v_lshlrev_b32_e32 v69, 16, v122
	v_and_b32_e32 v70, 0xffff0000, v122
	v_lshlrev_b32_e32 v71, 16, v123
	v_and_b32_e32 v72, 0xffff0000, v123
	s_waitcnt vmcnt(25)
	v_lshlrev_b32_e32 v54, 16, v124
	v_and_b32_e32 v53, 0xffff0000, v124
	v_lshlrev_b32_e32 v51, 16, v125
	v_and_b32_e32 v50, 0xffff0000, v125
	v_mul_f32_e32 v34, v22, v60
	v_mul_f32_e32 v35, v23, v59
	v_fmac_f32_e32 v34, v14, v62
	v_fmac_f32_e32 v35, v15, v67
	v_fmac_f32_e32 v34, v30, v54
	v_fmac_f32_e32 v35, v31, v53
	v_mul_f32_e32 v2, v34, v2
	v_mul_f32_e32 v34, v35, v42
	v_mul_f32_e32 v35, v24, v58
	v_lshlrev_b32_e32 v49, 16, v126
	v_and_b32_e32 v48, 0xffff0000, v126
	v_fmac_f32_e32 v35, v16, v65
	v_mul_f32_e32 v36, v25, v57
	v_fmac_f32_e32 v36, v17, v66
	v_fmac_f32_e32 v35, v32, v51
	v_mul_f32_e32 v42, v19, v55
	v_lshlrev_b32_e32 v47, 16, v127
	v_and_b32_e32 v46, 0xffff0000, v127
	v_mul_f32_e32 v35, v35, v43
	v_fmac_f32_e32 v36, v33, v50
	v_mul_f32_e32 v37, v18, v56
	v_fmac_f32_e32 v42, v11, v64
	v_mul_f32_e32 v43, v20, v52
	v_mul_f32_e32 v36, v36, v44
	v_fmac_f32_e32 v37, v10, v63
	v_fmac_f32_e32 v42, v27, v48
	v_fmac_f32_e32 v43, v12, v61
	v_mul_f32_e32 v44, v21, v45
	v_fmac_f32_e32 v37, v26, v49
	v_mul_f32_e32 v42, v42, v70
	v_fmac_f32_e32 v44, v13, v68
	v_fmac_f32_e32 v43, v28, v47
	v_mul_f32_e32 v37, v37, v69
	v_mul_f32_e32 v43, v43, v71
	v_fmac_f32_e32 v44, v29, v46
	v_cvt_pk_bf16_f32 v34, v2, v34
	v_cvt_pk_bf16_f32 v35, v35, v36
	v_cvt_pk_bf16_f32 v36, v37, v42
	v_add_co_u32_e32 v42, vcc, s2, v38
	v_mul_f32_e32 v44, v44, v72
	v_cvt_pk_bf16_f32 v37, v43, v44
	s_nop 0
	v_addc_co_u32_e32 v43, vcc, 0, v39, vcc
	s_mov_b32 s2, 0x9303000
	v_add_co_u32_e32 v38, vcc, s2, v38
	global_store_dwordx4 v[40:41], v[34:37], off
	s_nop 0
	v_addc_co_u32_e32 v39, vcc, 0, v39, vcc
	s_waitcnt vmcnt(25)
; __device__ __forceinline__ uint4 pack8(const float* f) { uint4 o; o.x = pk2(f[0], f[1]); o.y = pk2(f[2], f[3]); o.z = pk2(f[4], f[5]); o.w = pk2(f[6], f[7]); return o; }
; __device__ __forceinline__ void phase_sc_conv(const Args& a, int j) {
;     ...
; #pragma unroll 4
;         for (int r = 0; r < RUN; ++r) {
;             bf16_t* p = BIG + (size_t)(row0 + r) * LD + c0;
;             float gb[8], cur[8], o[8];
;             unpack8(*(const uint4*)p, gb); unpack8(*(const uint4*)(p + 1024), cur);
; #pragma unroll
;             for (int e = 0; e < 8; ++e) { o[e] = gb[e] * (w0[e] * g0[e] + w1[e] * g1[e] + w2[e] * cur[e]); g0[e] = g1[e]; g1[e] = cur[e]; }
;             *(uint4*)p = pack8(o);
;         }
	v_lshlrev_b32_e32 v65, 16, v128
	s_waitcnt vmcnt(24)
	v_lshlrev_b32_e32 v44, 16, v132
	v_and_b32_e32 v43, 0xffff0000, v132
	v_mul_f32_e32 v66, v22, v54
	v_fmac_f32_e32 v66, v14, v60
	v_mul_f32_e32 v60, v23, v53
	v_fmac_f32_e32 v66, v30, v44
	v_fmac_f32_e32 v60, v15, v59
	v_mul_f32_e32 v59, v66, v65
	v_mul_f32_e32 v65, v24, v51
	v_fmac_f32_e32 v65, v16, v58
	v_mul_f32_e32 v58, v25, v50
	v_and_b32_e32 v2, 0xffff0000, v133
	v_fmac_f32_e32 v58, v17, v57
	v_and_b32_e32 v63, 0xffff0000, v129
	v_fmac_f32_e32 v58, v33, v2
	v_mul_f32_e32 v58, v58, v63
	v_mul_f32_e32 v63, v18, v49
	v_fmac_f32_e32 v63, v10, v56
	v_mul_f32_e32 v56, v19, v48
	v_lshlrev_b32_e32 v41, 16, v131
	v_and_b32_e32 v40, 0xffff0000, v131
	v_and_b32_e32 v37, 0xffff0000, v134
	v_fmac_f32_e32 v56, v11, v55
	v_and_b32_e32 v61, 0xffff0000, v130
	v_fmac_f32_e32 v56, v27, v37
	v_mul_f32_e32 v61, v56, v61
	v_mul_f32_e32 v56, v20, v47
	v_lshlrev_b32_e32 v42, 16, v133
	v_fmac_f32_e32 v56, v12, v52
	v_mul_f32_e32 v52, v21, v46
	v_and_b32_e32 v70, 0xffff0000, v128
	v_lshlrev_b32_e32 v64, 16, v129
	v_lshlrev_b32_e32 v62, 16, v130
	v_lshlrev_b32_e32 v36, 16, v134
	v_lshlrev_b32_e32 v34, 16, v135
	v_and_b32_e32 v35, 0xffff0000, v135
	v_fmac_f32_e32 v65, v32, v42
	v_fmac_f32_e32 v52, v13, v45
	v_fmac_f32_e32 v60, v31, v43
	v_mul_f32_e32 v57, v65, v64
	v_fmac_f32_e32 v63, v26, v36
	v_fmac_f32_e32 v56, v28, v34
	v_fmac_f32_e32 v52, v29, v35
	v_mul_f32_e32 v60, v60, v70
	v_mul_f32_e32 v55, v63, v62
	v_mul_f32_e32 v41, v56, v41
	v_mul_f32_e32 v40, v52, v40
	v_cvt_pk_bf16_f32 v56, v59, v60
	v_cvt_pk_bf16_f32 v57, v57, v58
	v_cvt_pk_bf16_f32 v58, v55, v61
	v_cvt_pk_bf16_f32 v59, v41, v40
	global_store_dwordx4 v[38:39], v[56:59], off offset:-4096
	s_waitcnt vmcnt(24)
	v_lshlrev_b32_e32 v40, 16, v136
	v_and_b32_e32 v41, 0xffff0000, v136
	v_lshlrev_b32_e32 v45, 16, v137
	v_and_b32_e32 v52, 0xffff0000, v137
	v_lshlrev_b32_e32 v55, 16, v138
	v_and_b32_e32 v60, 0xffff0000, v138
	v_lshlrev_b32_e32 v69, 16, v139
	v_and_b32_e32 v70, 0xffff0000, v139
	s_waitcnt vmcnt(23)
	v_lshlrev_b32_e32 v62, 16, v140
	v_and_b32_e32 v67, 0xffff0000, v140
	v_mul_f32_e32 v56, v22, v44
	v_fmac_f32_e32 v56, v14, v54
	v_mul_f32_e32 v54, v23, v43
	v_fmac_f32_e32 v54, v15, v53
	v_mul_f32_e32 v53, v24, v42
	v_fmac_f32_e32 v53, v16, v51
	v_mul_f32_e32 v51, v25, v2
	v_and_b32_e32 v66, 0xffff0000, v141
	v_fmac_f32_e32 v51, v17, v50
	v_fmac_f32_e32 v51, v33, v66
	v_mul_f32_e32 v50, v51, v52
	v_mul_f32_e32 v51, v18, v36
	v_lshlrev_b32_e32 v63, 16, v142
	v_fmac_f32_e32 v51, v10, v49
	v_mul_f32_e32 v49, v19, v37
	v_fmac_f32_e32 v51, v26, v63
	v_fmac_f32_e32 v49, v11, v48
	v_mul_f32_e32 v48, v51, v55
	v_mul_f32_e32 v51, v20, v34
	v_and_b32_e32 v64, 0xffff0000, v142
	v_fmac_f32_e32 v51, v12, v47
	v_mul_f32_e32 v47, v21, v35
	v_lshlrev_b32_e32 v65, 16, v141
	v_lshlrev_b32_e32 v61, 16, v143
	v_and_b32_e32 v68, 0xffff0000, v143
	v_fmac_f32_e32 v49, v27, v64
	v_fmac_f32_e32 v47, v13, v46
	v_fmac_f32_e32 v56, v30, v62
	v_fmac_f32_e32 v54, v31, v67
	v_fmac_f32_e32 v53, v32, v65
	v_mul_f32_e32 v49, v49, v60
	v_fmac_f32_e32 v51, v28, v61
	v_fmac_f32_e32 v47, v29, v68
	v_mul_f32_e32 v40, v56, v40
	v_mul_f32_e32 v41, v54, v41
	v_mul_f32_e32 v45, v53, v45
	v_mul_f32_e32 v51, v51, v69
	v_mul_f32_e32 v52, v47, v70
	v_cvt_pk_bf16_f32 v46, v40, v41
	v_cvt_pk_bf16_f32 v47, v45, v50
	v_cvt_pk_bf16_f32 v48, v48, v49
	v_cvt_pk_bf16_f32 v49, v51, v52
	global_store_dwordx4 v[38:39], v[46:49], off
	v_lshl_add_u64 v[38:39], v[4:5], 0, s[12:13]
	v_add_co_u32_e32 v50, vcc, s26, v38
	s_mov_b32 s2, 0x9302000
	s_nop 0
	v_addc_co_u32_e32 v51, vcc, 0, v39, vcc
	v_add_co_u32_e32 v40, vcc, s18, v38
	s_add_u32 s12, s12, 0x4000
	s_nop 0
	v_addc_co_u32_e32 v41, vcc, 0, v39, vcc
	v_add_co_u32_e32 v108, vcc, 0x9303000, v38
	s_nop 1
	v_addc_co_u32_e32 v109, vcc, 0, v39, vcc
	s_addc_u32 s13, s13, 0
	s_waitcnt vmcnt(23)
	v_lshlrev_b32_e32 v53, 16, v144
	v_and_b32_e32 v54, 0xffff0000, v144
	v_lshlrev_b32_e32 v69, 16, v145
	v_and_b32_e32 v70, 0xffff0000, v145
	v_lshlrev_b32_e32 v71, 16, v146
	v_and_b32_e32 v72, 0xffff0000, v146
	v_lshlrev_b32_e32 v73, 16, v147
	v_and_b32_e32 v74, 0xffff0000, v147
	s_waitcnt vmcnt(22)
	v_lshlrev_b32_e32 v60, 16, v148
	v_and_b32_e32 v59, 0xffff0000, v148
	v_mul_f32_e32 v46, v22, v62
	v_fmac_f32_e32 v46, v14, v44
	v_mul_f32_e32 v44, v23, v67
	v_fmac_f32_e32 v46, v30, v60
	v_fmac_f32_e32 v44, v15, v43
	v_mul_f32_e32 v43, v46, v53
	v_mul_f32_e32 v46, v24, v65
	v_lshlrev_b32_e32 v58, 16, v149
	v_fmac_f32_e32 v46, v16, v42
	v_mul_f32_e32 v42, v25, v66
	v_fmac_f32_e32 v46, v32, v58
	v_fmac_f32_e32 v42, v17, v2
	v_mul_f32_e32 v2, v46, v69
	v_mul_f32_e32 v46, v18, v63
	v_lshlrev_b32_e32 v56, 16, v150
	v_fmac_f32_e32 v46, v10, v36
	v_mul_f32_e32 v36, v19, v64
	v_fmac_f32_e32 v46, v26, v56
	v_fmac_f32_e32 v36, v11, v37
	v_mul_f32_e32 v37, v46, v71
	v_mul_f32_e32 v46, v20, v61
	v_and_b32_e32 v55, 0xffff0000, v150
	v_fmac_f32_e32 v46, v12, v34
	v_mul_f32_e32 v34, v21, v68
	v_and_b32_e32 v57, 0xffff0000, v149
	v_lshlrev_b32_e32 v52, 16, v151
	v_and_b32_e32 v45, 0xffff0000, v151
	v_fmac_f32_e32 v36, v27, v55
	v_fmac_f32_e32 v34, v13, v35
	v_fmac_f32_e32 v44, v31, v59
	v_fmac_f32_e32 v42, v33, v57
	v_mul_f32_e32 v36, v36, v72
	v_fmac_f32_e32 v46, v28, v52
	v_fmac_f32_e32 v34, v29, v45
	v_mul_f32_e32 v44, v44, v54
	v_mul_f32_e32 v42, v42, v70
	v_mul_f32_e32 v46, v46, v73
	v_mul_f32_e32 v47, v34, v74
	v_cvt_pk_bf16_f32 v34, v43, v44
	v_cvt_pk_bf16_f32 v35, v2, v42
	v_cvt_pk_bf16_f32 v36, v37, v36
	v_cvt_pk_bf16_f32 v37, v46, v47
	global_store_dwordx4 v[40:41], v[34:37], off offset:-4096
	s_waitcnt vmcnt(22)
; __device__ __forceinline__ uint4 pack8(const float* f) { uint4 o; o.x = pk2(f[0], f[1]); o.y = pk2(f[2], f[3]); o.z = pk2(f[4], f[5]); o.w = pk2(f[6], f[7]); return o; }
; __device__ __forceinline__ void phase_sc_conv(const Args& a, int j) {
;     ...
; #pragma unroll 4
;         for (int r = 0; r < RUN; ++r) {
;             bf16_t* p = BIG + (size_t)(row0 + r) * LD + c0;
;             float gb[8], cur[8], o[8];
;             unpack8(*(const uint4*)p, gb); unpack8(*(const uint4*)(p + 1024), cur);
; #pragma unroll
;             for (int e = 0; e < 8; ++e) { o[e] = gb[e] * (w0[e] * g0[e] + w1[e] * g1[e] + w2[e] * cur[e]); g0[e] = g1[e]; g1[e] = cur[e]; }
;             *(uint4*)p = pack8(o);
;         }
	v_lshlrev_b32_e32 v2, 16, v152
	v_and_b32_e32 v42, 0xffff0000, v152
	v_lshlrev_b32_e32 v43, 16, v153
	v_and_b32_e32 v44, 0xffff0000, v153
	v_lshlrev_b32_e32 v69, 16, v154
	v_and_b32_e32 v70, 0xffff0000, v154
	v_lshlrev_b32_e32 v71, 16, v155
	v_and_b32_e32 v72, 0xffff0000, v155
	s_waitcnt vmcnt(21)
	v_lshlrev_b32_e32 v54, 16, v156
	v_and_b32_e32 v53, 0xffff0000, v156
	v_lshlrev_b32_e32 v51, 16, v157
	v_and_b32_e32 v50, 0xffff0000, v157
	v_mul_f32_e32 v34, v22, v60
	v_mul_f32_e32 v35, v23, v59
	v_fmac_f32_e32 v34, v14, v62
	v_fmac_f32_e32 v35, v15, v67
	v_fmac_f32_e32 v34, v30, v54
	v_fmac_f32_e32 v35, v31, v53
	v_mul_f32_e32 v2, v34, v2
	v_mul_f32_e32 v34, v35, v42
	v_mul_f32_e32 v35, v24, v58
	v_lshlrev_b32_e32 v49, 16, v158
	v_and_b32_e32 v48, 0xffff0000, v158
	v_fmac_f32_e32 v35, v16, v65
	v_mul_f32_e32 v36, v25, v57
	v_fmac_f32_e32 v36, v17, v66
	v_fmac_f32_e32 v35, v32, v51
	v_mul_f32_e32 v42, v19, v55
	v_lshlrev_b32_e32 v47, 16, v159
	v_and_b32_e32 v46, 0xffff0000, v159
	v_mul_f32_e32 v35, v35, v43
	v_fmac_f32_e32 v36, v33, v50
	v_mul_f32_e32 v37, v18, v56
	v_fmac_f32_e32 v42, v11, v64
	v_mul_f32_e32 v43, v20, v52
	v_mul_f32_e32 v36, v36, v44
	v_fmac_f32_e32 v37, v10, v63
	v_fmac_f32_e32 v42, v27, v48
	v_fmac_f32_e32 v43, v12, v61
	v_mul_f32_e32 v44, v21, v45
	v_fmac_f32_e32 v37, v26, v49
	v_mul_f32_e32 v42, v42, v70
	v_fmac_f32_e32 v44, v13, v68
	v_fmac_f32_e32 v43, v28, v47
	v_mul_f32_e32 v37, v37, v69
	v_mul_f32_e32 v43, v43, v71
	v_fmac_f32_e32 v44, v29, v46
	v_cvt_pk_bf16_f32 v34, v2, v34
	v_cvt_pk_bf16_f32 v35, v35, v36
	v_cvt_pk_bf16_f32 v36, v37, v42
	v_add_co_u32_e32 v42, vcc, s2, v38
	v_mul_f32_e32 v44, v44, v72
	v_cvt_pk_bf16_f32 v37, v43, v44
	s_nop 0
	v_addc_co_u32_e32 v43, vcc, 0, v39, vcc
	s_mov_b32 s2, 0x9303000
	v_add_co_u32_e32 v38, vcc, s2, v38
	global_store_dwordx4 v[40:41], v[34:37], off
	s_nop 0
	v_addc_co_u32_e32 v39, vcc, 0, v39, vcc
	s_waitcnt vmcnt(21)
	v_lshlrev_b32_e32 v65, 16, v160
	s_waitcnt vmcnt(20)
	v_lshlrev_b32_e32 v44, 16, v164
	v_and_b32_e32 v43, 0xffff0000, v164
	v_mul_f32_e32 v66, v22, v54
	v_fmac_f32_e32 v66, v14, v60
	v_mul_f32_e32 v60, v23, v53
	v_fmac_f32_e32 v66, v30, v44
	v_fmac_f32_e32 v60, v15, v59
	v_mul_f32_e32 v59, v66, v65
	v_mul_f32_e32 v65, v24, v51
	v_fmac_f32_e32 v65, v16, v58
	v_mul_f32_e32 v58, v25, v50
	v_and_b32_e32 v2, 0xffff0000, v165
	v_fmac_f32_e32 v58, v17, v57
	v_and_b32_e32 v63, 0xffff0000, v161
	v_fmac_f32_e32 v58, v33, v2
	v_mul_f32_e32 v58, v58, v63
	v_mul_f32_e32 v63, v18, v49
	v_fmac_f32_e32 v63, v10, v56
	v_mul_f32_e32 v56, v19, v48
	v_lshlrev_b32_e32 v41, 16, v163
	v_and_b32_e32 v40, 0xffff0000, v163
	v_and_b32_e32 v37, 0xffff0000, v166
	v_fmac_f32_e32 v56, v11, v55
	v_and_b32_e32 v61, 0xffff0000, v162
	v_fmac_f32_e32 v56, v27, v37
	v_mul_f32_e32 v61, v56, v61
	v_mul_f32_e32 v56, v20, v47
	v_lshlrev_b32_e32 v42, 16, v165
	v_fmac_f32_e32 v56, v12, v52
	v_mul_f32_e32 v52, v21, v46
	v_and_b32_e32 v70, 0xffff0000, v160
	v_lshlrev_b32_e32 v64, 16, v161
	v_lshlrev_b32_e32 v62, 16, v162
	v_lshlrev_b32_e32 v36, 16, v166
	v_lshlrev_b32_e32 v34, 16, v167
	v_and_b32_e32 v35, 0xffff0000, v167
	v_fmac_f32_e32 v65, v32, v42
	v_fmac_f32_e32 v52, v13, v45
	v_fmac_f32_e32 v60, v31, v43
	v_mul_f32_e32 v57, v65, v64
	v_fmac_f32_e32 v63, v26, v36
	v_fmac_f32_e32 v56, v28, v34
	v_fmac_f32_e32 v52, v29, v35
	v_mul_f32_e32 v60, v60, v70
	v_mul_f32_e32 v55, v63, v62
	v_mul_f32_e32 v41, v56, v41
	v_mul_f32_e32 v40, v52, v40
	v_cvt_pk_bf16_f32 v56, v59, v60
	v_cvt_pk_bf16_f32 v57, v57, v58
	v_cvt_pk_bf16_f32 v58, v55, v61
	v_cvt_pk_bf16_f32 v59, v41, v40
	global_store_dwordx4 v[38:39], v[56:59], off offset:-4096
	s_waitcnt vmcnt(20)
	v_lshlrev_b32_e32 v40, 16, v176
	v_and_b32_e32 v41, 0xffff0000, v176
	v_lshlrev_b32_e32 v45, 16, v177
	v_and_b32_e32 v52, 0xffff0000, v177
	v_lshlrev_b32_e32 v55, 16, v178
	v_and_b32_e32 v60, 0xffff0000, v178
	v_lshlrev_b32_e32 v69, 16, v179
	v_and_b32_e32 v70, 0xffff0000, v179
	s_waitcnt vmcnt(19)
	v_lshlrev_b32_e32 v62, 16, v180
	v_and_b32_e32 v67, 0xffff0000, v180
	v_mul_f32_e32 v56, v22, v44
	v_fmac_f32_e32 v56, v14, v54
	v_mul_f32_e32 v54, v23, v43
	v_fmac_f32_e32 v54, v15, v53
	v_mul_f32_e32 v53, v24, v42
	v_fmac_f32_e32 v53, v16, v51
	v_mul_f32_e32 v51, v25, v2
	v_and_b32_e32 v66, 0xffff0000, v181
	v_fmac_f32_e32 v51, v17, v50
	v_fmac_f32_e32 v51, v33, v66
	v_mul_f32_e32 v50, v51, v52
	v_mul_f32_e32 v51, v18, v36
	v_lshlrev_b32_e32 v63, 16, v182
	v_fmac_f32_e32 v51, v10, v49
	v_mul_f32_e32 v49, v19, v37
	v_fmac_f32_e32 v51, v26, v63
	v_fmac_f32_e32 v49, v11, v48
	v_mul_f32_e32 v48, v51, v55
	v_mul_f32_e32 v51, v20, v34
	v_and_b32_e32 v64, 0xffff0000, v182
	v_fmac_f32_e32 v51, v12, v47
	v_mul_f32_e32 v47, v21, v35
	v_lshlrev_b32_e32 v65, 16, v181
	v_lshlrev_b32_e32 v61, 16, v183
	v_and_b32_e32 v68, 0xffff0000, v183
	v_fmac_f32_e32 v49, v27, v64
	v_fmac_f32_e32 v47, v13, v46
	v_fmac_f32_e32 v56, v30, v62
	v_fmac_f32_e32 v54, v31, v67
	v_fmac_f32_e32 v53, v32, v65
	v_mul_f32_e32 v49, v49, v60
	v_fmac_f32_e32 v51, v28, v61
	v_fmac_f32_e32 v47, v29, v68
	v_mul_f32_e32 v40, v56, v40
	v_mul_f32_e32 v41, v54, v41
	v_mul_f32_e32 v45, v53, v45
	v_mul_f32_e32 v51, v51, v69
	v_mul_f32_e32 v52, v47, v70
	v_cvt_pk_bf16_f32 v46, v40, v41
	v_cvt_pk_bf16_f32 v47, v45, v50
	v_cvt_pk_bf16_f32 v48, v48, v49
	v_cvt_pk_bf16_f32 v49, v51, v52
	global_store_dwordx4 v[38:39], v[46:49], off
	v_lshl_add_u64 v[38:39], v[4:5], 0, s[12:13]
	v_add_co_u32_e32 v50, vcc, s26, v38
	s_mov_b32 s2, 0x9302000
	s_nop 0
	v_addc_co_u32_e32 v51, vcc, 0, v39, vcc
	v_add_co_u32_e32 v40, vcc, s18, v38
	s_add_u32 s12, s12, 0x4000
	s_nop 0
	v_addc_co_u32_e32 v41, vcc, 0, v39, vcc
	v_add_co_u32_e32 v108, vcc, 0x9303000, v38
	s_nop 1
	v_addc_co_u32_e32 v109, vcc, 0, v39, vcc
	s_addc_u32 s13, s13, 0
	s_waitcnt vmcnt(19)
; __device__ __forceinline__ uint4 pack8(const float* f) { uint4 o; o.x = pk2(f[0], f[1]); o.y = pk2(f[2], f[3]); o.z = pk2(f[4], f[5]); o.w = pk2(f[6], f[7]); return o; }
; __device__ __forceinline__ void phase_sc_conv(const Args& a, int j) {
;     ...
; #pragma unroll 4
;         for (int r = 0; r < RUN; ++r) {
;             bf16_t* p = BIG + (size_t)(row0 + r) * LD + c0;
;             float gb[8], cur[8], o[8];
;             unpack8(*(const uint4*)p, gb); unpack8(*(const uint4*)(p + 1024), cur);
; #pragma unroll
;             for (int e = 0; e < 8; ++e) { o[e] = gb[e] * (w0[e] * g0[e] + w1[e] * g1[e] + w2[e] * cur[e]); g0[e] = g1[e]; g1[e] = cur[e]; }
;             *(uint4*)p = pack8(o);
;         }
	v_lshlrev_b32_e32 v53, 16, v184
	v_and_b32_e32 v54, 0xffff0000, v184
	v_lshlrev_b32_e32 v69, 16, v185
	v_and_b32_e32 v70, 0xffff0000, v185
	v_lshlrev_b32_e32 v71, 16, v186
	v_and_b32_e32 v72, 0xffff0000, v186
	v_lshlrev_b32_e32 v73, 16, v187
	v_and_b32_e32 v74, 0xffff0000, v187
	s_waitcnt vmcnt(18)
	v_lshlrev_b32_e32 v60, 16, v188
	v_and_b32_e32 v59, 0xffff0000, v188
	v_mul_f32_e32 v46, v22, v62
	v_fmac_f32_e32 v46, v14, v44
	v_mul_f32_e32 v44, v23, v67
	v_fmac_f32_e32 v46, v30, v60
	v_fmac_f32_e32 v44, v15, v43
	v_mul_f32_e32 v43, v46, v53
	v_mul_f32_e32 v46, v24, v65
	v_lshlrev_b32_e32 v58, 16, v189
	v_fmac_f32_e32 v46, v16, v42
	v_mul_f32_e32 v42, v25, v66
	v_fmac_f32_e32 v46, v32, v58
	v_fmac_f32_e32 v42, v17, v2
	v_mul_f32_e32 v2, v46, v69
	v_mul_f32_e32 v46, v18, v63
	v_lshlrev_b32_e32 v56, 16, v190
	v_fmac_f32_e32 v46, v10, v36
	v_mul_f32_e32 v36, v19, v64
	v_fmac_f32_e32 v46, v26, v56
	v_fmac_f32_e32 v36, v11, v37
	v_mul_f32_e32 v37, v46, v71
	v_mul_f32_e32 v46, v20, v61
	v_and_b32_e32 v55, 0xffff0000, v190
	v_fmac_f32_e32 v46, v12, v34
	v_mul_f32_e32 v34, v21, v68
	v_and_b32_e32 v57, 0xffff0000, v189
	v_lshlrev_b32_e32 v52, 16, v191
	v_and_b32_e32 v45, 0xffff0000, v191
	v_fmac_f32_e32 v36, v27, v55
	v_fmac_f32_e32 v34, v13, v35
	v_fmac_f32_e32 v44, v31, v59
	v_fmac_f32_e32 v42, v33, v57
	v_mul_f32_e32 v36, v36, v72
	v_fmac_f32_e32 v46, v28, v52
	v_fmac_f32_e32 v34, v29, v45
	v_mul_f32_e32 v44, v44, v54
	v_mul_f32_e32 v42, v42, v70
	v_mul_f32_e32 v46, v46, v73
	v_mul_f32_e32 v47, v34, v74
	v_cvt_pk_bf16_f32 v34, v43, v44
	v_cvt_pk_bf16_f32 v35, v2, v42
	v_cvt_pk_bf16_f32 v36, v37, v36
	v_cvt_pk_bf16_f32 v37, v46, v47
	global_store_dwordx4 v[40:41], v[34:37], off offset:-4096
	s_waitcnt vmcnt(18)
	v_lshlrev_b32_e32 v2, 16, v192
	v_and_b32_e32 v42, 0xffff0000, v192
	v_lshlrev_b32_e32 v43, 16, v193
	v_and_b32_e32 v44, 0xffff0000, v193
	v_lshlrev_b32_e32 v69, 16, v194
	v_and_b32_e32 v70, 0xffff0000, v194
	v_lshlrev_b32_e32 v71, 16, v195
	v_and_b32_e32 v72, 0xffff0000, v195
	s_waitcnt vmcnt(17)
	v_lshlrev_b32_e32 v54, 16, v196
	v_and_b32_e32 v53, 0xffff0000, v196
	v_lshlrev_b32_e32 v51, 16, v197
	v_and_b32_e32 v50, 0xffff0000, v197
	v_mul_f32_e32 v34, v22, v60
	v_mul_f32_e32 v35, v23, v59
	v_fmac_f32_e32 v34, v14, v62
	v_fmac_f32_e32 v35, v15, v67
	v_fmac_f32_e32 v34, v30, v54
	v_fmac_f32_e32 v35, v31, v53
	v_mul_f32_e32 v2, v34, v2
	v_mul_f32_e32 v34, v35, v42
	v_mul_f32_e32 v35, v24, v58
	v_lshlrev_b32_e32 v49, 16, v198
	v_and_b32_e32 v48, 0xffff0000, v198
	v_fmac_f32_e32 v35, v16, v65
	v_mul_f32_e32 v36, v25, v57
	v_fmac_f32_e32 v36, v17, v66
	v_fmac_f32_e32 v35, v32, v51
	v_mul_f32_e32 v42, v19, v55
	v_lshlrev_b32_e32 v47, 16, v199
	v_and_b32_e32 v46, 0xffff0000, v199
	v_mul_f32_e32 v35, v35, v43
	v_fmac_f32_e32 v36, v33, v50
	v_mul_f32_e32 v37, v18, v56
	v_fmac_f32_e32 v42, v11, v64
	v_mul_f32_e32 v43, v20, v52
	v_mul_f32_e32 v36, v36, v44
	v_fmac_f32_e32 v37, v10, v63
	v_fmac_f32_e32 v42, v27, v48
	v_fmac_f32_e32 v43, v12, v61
	v_mul_f32_e32 v44, v21, v45
	v_fmac_f32_e32 v37, v26, v49
	v_mul_f32_e32 v42, v42, v70
	v_fmac_f32_e32 v44, v13, v68
	v_fmac_f32_e32 v43, v28, v47
	v_mul_f32_e32 v37, v37, v69
	v_mul_f32_e32 v43, v43, v71
	v_fmac_f32_e32 v44, v29, v46
	v_cvt_pk_bf16_f32 v34, v2, v34
	v_cvt_pk_bf16_f32 v35, v35, v36
	v_cvt_pk_bf16_f32 v36, v37, v42
	v_add_co_u32_e32 v42, vcc, s2, v38
	v_mul_f32_e32 v44, v44, v72
	v_cvt_pk_bf16_f32 v37, v43, v44
	s_nop 0
	v_addc_co_u32_e32 v43, vcc, 0, v39, vcc
	s_mov_b32 s2, 0x9303000
	v_add_co_u32_e32 v38, vcc, s2, v38
	global_store_dwordx4 v[40:41], v[34:37], off
	s_nop 0
	v_addc_co_u32_e32 v39, vcc, 0, v39, vcc
	s_waitcnt vmcnt(17)
; __device__ __forceinline__ uint4 pack8(const float* f) { uint4 o; o.x = pk2(f[0], f[1]); o.y = pk2(f[2], f[3]); o.z = pk2(f[4], f[5]); o.w = pk2(f[6], f[7]); return o; }
; __device__ __forceinline__ void phase_sc_conv(const Args& a, int j) {
;     ...
;     for (int it = gt; it < NITEMS; it += NGT) {
;     ...
; #pragma unroll 4
;         for (int r = 0; r < RUN; ++r) {
;             bf16_t* p = BIG + (size_t)(row0 + r) * LD + c0;
;             float gb[8], cur[8], o[8];
;             unpack8(*(const uint4*)p, gb); unpack8(*(const uint4*)(p + 1024), cur);
; #pragma unroll
;             for (int e = 0; e < 8; ++e) { o[e] = gb[e] * (w0[e] * g0[e] + w1[e] * g1[e] + w2[e] * cur[e]); g0[e] = g1[e]; g1[e] = cur[e]; }
;             *(uint4*)p = pack8(o);
;         }
	v_lshlrev_b32_e32 v65, 16, v200
	s_waitcnt vmcnt(16)
	v_lshlrev_b32_e32 v44, 16, v220
	v_and_b32_e32 v43, 0xffff0000, v220
	v_mul_f32_e32 v66, v22, v54
	v_fmac_f32_e32 v66, v14, v60
	v_mul_f32_e32 v60, v23, v53
	v_fmac_f32_e32 v66, v30, v44
	v_fmac_f32_e32 v60, v15, v59
	v_mul_f32_e32 v59, v66, v65
	v_mul_f32_e32 v65, v24, v51
	v_fmac_f32_e32 v65, v16, v58
	v_mul_f32_e32 v58, v25, v50
	v_and_b32_e32 v2, 0xffff0000, v221
	v_fmac_f32_e32 v58, v17, v57
	v_and_b32_e32 v63, 0xffff0000, v201
	v_fmac_f32_e32 v58, v33, v2
	v_mul_f32_e32 v58, v58, v63
	v_mul_f32_e32 v63, v18, v49
	v_fmac_f32_e32 v63, v10, v56
	v_mul_f32_e32 v56, v19, v48
	v_lshlrev_b32_e32 v41, 16, v203
	v_and_b32_e32 v40, 0xffff0000, v203
	v_and_b32_e32 v37, 0xffff0000, v222
	v_fmac_f32_e32 v56, v11, v55
	v_and_b32_e32 v61, 0xffff0000, v202
	v_fmac_f32_e32 v56, v27, v37
	v_mul_f32_e32 v61, v56, v61
	v_mul_f32_e32 v56, v20, v47
	v_lshlrev_b32_e32 v42, 16, v221
	v_fmac_f32_e32 v56, v12, v52
	v_mul_f32_e32 v52, v21, v46
	v_and_b32_e32 v70, 0xffff0000, v200
	v_lshlrev_b32_e32 v64, 16, v201
	v_lshlrev_b32_e32 v62, 16, v202
	v_lshlrev_b32_e32 v36, 16, v222
	v_lshlrev_b32_e32 v34, 16, v223
	v_and_b32_e32 v35, 0xffff0000, v223
	v_fmac_f32_e32 v65, v32, v42
	v_fmac_f32_e32 v52, v13, v45
	v_fmac_f32_e32 v60, v31, v43
	v_mul_f32_e32 v57, v65, v64
	v_fmac_f32_e32 v63, v26, v36
	v_fmac_f32_e32 v56, v28, v34
	v_fmac_f32_e32 v52, v29, v35
	v_mul_f32_e32 v60, v60, v70
	v_mul_f32_e32 v55, v63, v62
	v_mul_f32_e32 v41, v56, v41
	v_mul_f32_e32 v40, v52, v40
	v_cvt_pk_bf16_f32 v56, v59, v60
	v_cvt_pk_bf16_f32 v57, v57, v58
	v_cvt_pk_bf16_f32 v58, v55, v61
	v_cvt_pk_bf16_f32 v59, v41, v40
	global_store_dwordx4 v[38:39], v[56:59], off offset:-4096
	s_waitcnt vmcnt(16)
	v_lshlrev_b32_e32 v40, 16, v224
	v_and_b32_e32 v41, 0xffff0000, v224
	v_lshlrev_b32_e32 v45, 16, v225
	v_and_b32_e32 v52, 0xffff0000, v225
	v_lshlrev_b32_e32 v55, 16, v226
	v_and_b32_e32 v60, 0xffff0000, v226
	v_lshlrev_b32_e32 v69, 16, v227
	v_and_b32_e32 v70, 0xffff0000, v227
	s_waitcnt vmcnt(15)
	v_lshlrev_b32_e32 v62, 16, v228
	v_and_b32_e32 v67, 0xffff0000, v228
	v_mul_f32_e32 v56, v22, v44
	v_fmac_f32_e32 v56, v14, v54
	v_mul_f32_e32 v54, v23, v43
	v_fmac_f32_e32 v54, v15, v53
	v_mul_f32_e32 v53, v24, v42
	v_fmac_f32_e32 v53, v16, v51
	v_mul_f32_e32 v51, v25, v2
	v_and_b32_e32 v66, 0xffff0000, v229
	v_fmac_f32_e32 v51, v17, v50
	v_fmac_f32_e32 v51, v33, v66
	v_mul_f32_e32 v50, v51, v52
	v_mul_f32_e32 v51, v18, v36
	v_lshlrev_b32_e32 v63, 16, v230
	v_fmac_f32_e32 v51, v10, v49
	v_mul_f32_e32 v49, v19, v37
	v_fmac_f32_e32 v51, v26, v63
	v_fmac_f32_e32 v49, v11, v48
	v_mul_f32_e32 v48, v51, v55
	v_mul_f32_e32 v51, v20, v34
	v_and_b32_e32 v64, 0xffff0000, v230
	v_fmac_f32_e32 v51, v12, v47
	v_mul_f32_e32 v47, v21, v35
	v_lshlrev_b32_e32 v65, 16, v229
	v_lshlrev_b32_e32 v61, 16, v231
	v_and_b32_e32 v68, 0xffff0000, v231
	v_fmac_f32_e32 v49, v27, v64
	v_fmac_f32_e32 v47, v13, v46
	v_fmac_f32_e32 v56, v30, v62
	v_fmac_f32_e32 v54, v31, v67
	v_fmac_f32_e32 v53, v32, v65
	v_mul_f32_e32 v49, v49, v60
	v_fmac_f32_e32 v51, v28, v61
	v_fmac_f32_e32 v47, v29, v68
	v_mul_f32_e32 v40, v56, v40
	v_mul_f32_e32 v41, v54, v41
	v_mul_f32_e32 v45, v53, v45
	v_mul_f32_e32 v51, v51, v69
	v_mul_f32_e32 v52, v47, v70
	v_cvt_pk_bf16_f32 v46, v40, v41
	v_cvt_pk_bf16_f32 v47, v45, v50
	v_cvt_pk_bf16_f32 v48, v48, v49
	v_cvt_pk_bf16_f32 v49, v51, v52
	global_store_dwordx4 v[38:39], v[46:49], off
	v_add_u32_e32 v1, s90, v1
	s_mov_b32 s2, 0x1ffff
	v_cmp_lt_i32_e32 vcc, s2, v1
	s_or_b64 s[10:11], vcc, s[10:11]
	s_andn2_b64 exec, exec, s[10:11]
	s_cbranch_execnz .LBB0_757
